# SO7: chunk loop local edits - output rows packed with v_cvt_pk_bf16_f32 and immediate-offset stores, loop-head reads with immediate offsets, virtual tiles' stores with SGPR base + 32-bit row offsets (
# speedup vs baseline: 1.0169x; 1.0023x over previous
.LBB0_438:
	s_andn2_b64 vcc, exec, s[90:91]
	s_cbranch_vccnz .LBB0_446
	v_and_b32_e32 v38, 0x3e0, v135
	s_movk_i32 s10, 0xc00
	v_and_b32_e32 v37, 0x3e0, v133
	v_add3_u32 v86, v38, v127, s10
	s_movk_i32 s10, 0x800
	v_lshl_add_u32 v82, v128, 5, v127
	v_and_b32_e32 v36, 0x3e0, v131
	v_lshl_add_u32 v34, v125, 8, s35
	v_add3_u32 v87, v37, v127, s10
	s_movk_i32 s10, 0x400
	v_add_lshl_u32 v83, v34, v128, 1
	v_add_u32_e32 v84, 0x1c800, v82
	v_add_u32_e32 v85, s70, v82
	v_add3_u32 v88, v36, v127, s10
	s_mov_b32 s14, 0
	v_lshlrev_b32_e32 v106, 1, v128
	v_mov_b32_e32 v89, v127
	v_mov_b32_e32 v90, v82
	v_lshl_add_u32 v66, v134, 12, v106
	v_add_u32_e32 v68, 0x1000, v66
	v_add_u32_e32 v70, 0x2000, v66
	v_add_u32_e32 v72, 0x3000, v66
	v_add_u32_e32 v74, 0x8000, v66
	v_add_u32_e32 v76, 0x9000, v66
	v_add_u32_e32 v78, 0xa000, v66
	v_add_u32_e32 v80, 0xb000, v66
	s_branch .LBB0_441

.LBB0_441:
	v_add_u32_e32 v42, 0x22a00, v89
	ds_read_b128 v[34:37], v42
	ds_read_b128 v[38:41], v42 offset:32
	ds_read_b128 v[50:53], v42 offset:64
	ds_read_b128 v[54:57], v42 offset:96
	ds_read_b128 v[58:61], v42 offset:128
	ds_read_b128 v[62:65], v42 offset:160
	ds_read_b128 v[92:95], v42 offset:192
	ds_read_b128 v[96:99], v42 offset:224
	ds_read_b128 v[130:133], v82
	ds_read_b128 v[134:137], v88
	v_mov_b32_e32 v91, v82
	v_mov_b32_e32 v100, v90
	ds_read_b128 v[138:141], v87
	ds_read_b128 v[142:145], v86
	v_add_u32_e32 v46, 0x1a800, v90
	ds_read_b128 v[42:45], v85
	ds_read_b128 v[46:49], v46
	s_waitcnt lgkmcnt(13)
	v_pk_mul_f32 v[2:3], v[2:3], v[34:35]
	v_pk_mul_f32 v[4:5], v[4:5], v[36:37]
	s_waitcnt lgkmcnt(12)
	v_pk_mul_f32 v[6:7], v[6:7], v[38:39]
	s_waitcnt lgkmcnt(1)
	v_cndmask_b32_e64 v149, v45, 0, s[84:85]
	v_cndmask_b32_e64 v148, v44, 0, s[84:85]
	v_cndmask_b32_e64 v147, v43, 0, s[84:85]
	v_cndmask_b32_e64 v146, v42, 0, s[84:85]
	v_pk_mul_f32 v[8:9], v[8:9], v[40:41]
	v_pk_mul_f32 v[10:11], v[10:11], v[50:51]
	s_waitcnt lgkmcnt(0)
	v_mfma_f32_32x32x16_f16 v[34:49], v[46:49], v[146:149], 0
	v_mul_f32_e64 v12, v12, v52
	v_mul_f32_e64 v13, v13, v53
	v_cvt_pk_f16_f32 v50, v2, v3
	v_cvt_pk_f16_f32 v51, v4, v5
	v_cvt_pk_f16_f32 v52, v6, v7
	v_cvt_pk_f16_f32 v53, v8, v9
	v_pk_mul_f32 v[14:15], v[14:15], v[54:55]
	v_pk_mul_f32 v[16:17], v[16:17], v[56:57]
	v_mfma_f32_32x32x16_f16 v[34:49], v[130:133], v[50:53], v[34:49]
	v_cvt_pk_f16_f32 v50, v10, v11
	v_cvt_pk_f16_f32 v51, v12, v13
	v_cvt_pk_f16_f32 v52, v14, v15
	v_cvt_pk_f16_f32 v53, v16, v17
	v_mul_f32_e64 v18, v18, v58
	v_mul_f32_e64 v19, v19, v59
	v_pk_mul_f32 v[20:21], v[20:21], v[60:61]
	v_pk_mul_f32 v[22:23], v[22:23], v[62:63]
	v_mfma_f32_32x32x16_f16 v[34:49], v[134:137], v[50:53], v[34:49]
	v_mul_f32_e64 v24, v24, v64
	v_mul_f32_e64 v25, v25, v65
	v_cvt_pk_f16_f32 v50, v18, v19
	v_cvt_pk_f16_f32 v51, v20, v21
	v_cvt_pk_f16_f32 v52, v22, v23
	v_cvt_pk_f16_f32 v53, v24, v25
	v_pk_mul_f32 v[26:27], v[26:27], v[92:93]
	v_pk_mul_f32 v[28:29], v[28:29], v[94:95]
	v_mfma_f32_32x32x16_f16 v[34:49], v[138:141], v[50:53], v[34:49]
	v_mul_f32_e64 v30, v30, v96
	v_mul_f32_e64 v31, v31, v97
	v_mul_f32_e64 v32, v32, v98
	v_mul_f32_e64 v33, v33, v99
	v_add_u32_e32 v100, 0x1b800, v100
	v_cvt_pk_f16_f32 v50, v26, v27
	v_cvt_pk_f16_f32 v51, v28, v29
	v_cvt_pk_f16_f32 v52, v30, v31
	v_cvt_pk_f16_f32 v53, v32, v33
	ds_read_b128 v[54:57], v100
	v_add_u32_e32 v96, 0x14800, v91
	v_mfma_f32_32x32x16_f16 v[34:49], v[142:145], v[50:53], v[34:49]
	v_add_u32_e32 v97, 0, v84
	ds_read_b128 v[92:95], v97
	s_andn2_b64 vcc, exec, s[86:87]
	s_mov_b64 s[10:11], -1
	s_nop 7
	v_cvt_pk_f16_f32 v50, v34, v35
	v_cvt_pk_f16_f32 v51, v36, v37
	v_cvt_pk_f16_f32 v52, v38, v39
	v_cvt_pk_f16_f32 v53, v40, v41
	s_waitcnt lgkmcnt(1)
	s_nop 0
	v_mfma_f32_32x32x16_f16 v[50:65], v[54:57], v[50:53], 0
	s_nop 11
	ds_read_b128 v[58:61], v96
	v_add_u32_e32 v62, 0x15000, v91
	v_cvt_pk_f16_f32 v50, v50, v51
	v_cvt_pk_f16_f32 v51, v52, v53
	v_cvt_pk_f16_f32 v52, v54, v55
	v_cvt_pk_f16_f32 v53, v56, v57
	ds_read_b128 v[54:57], v97 offset:1024
	s_waitcnt lgkmcnt(1)
	v_mfma_f32_32x32x16_f16 v[2:17], v[58:61], v[50:53], v[2:17]
	ds_read_b128 v[58:61], v62
	v_add_u32_e32 v62, 0x14c00, v91
	ds_read_b128 v[62:65], v62
	s_waitcnt lgkmcnt(1)
	v_mfma_f32_32x32x16_f16 v[18:33], v[58:61], v[50:53], v[18:33]
	v_add_u32_e32 v58, 0x15400, v91
	ds_read_b128 v[58:61], v58
	v_mfma_f32_32x32x16_f16 v[34:49], v[92:95], v[50:53], v[34:49]
	s_waitcnt lgkmcnt(1)
	v_mfma_f32_32x32x16_f16 v[2:17], v[62:65], v[146:149], v[2:17]
	s_waitcnt lgkmcnt(0)
	v_mfma_f32_32x32x16_f16 v[18:33], v[58:61], v[146:149], v[18:33]
	v_mfma_f32_32x32x16_f16 v[34:49], v[54:57], v[146:149], v[34:49]
	s_cbranch_vccnz .LBB0_443
	s_nop 10
	v_add_u32_e32 v35, 0x20000, v83
	v_cvt_pk_bf16_f32 v34, v42, v43
	v_cvt_pk_bf16_f32 v36, v44, v45
	v_cvt_pk_bf16_f32 v37, v46, v47
	v_cvt_pk_bf16_f32 v38, v48, v49
	ds_write_b16 v35, v34
	ds_write_b16_d16_hi v35, v34 offset:128
	ds_write_b16 v35, v36 offset:256
	ds_write_b16_d16_hi v35, v36 offset:384
	ds_write_b16 v35, v37 offset:1024
	ds_write_b16_d16_hi v35, v37 offset:1152
	ds_write_b16 v35, v38 offset:1280
	ds_write_b16_d16_hi v35, v38 offset:1408
	s_mov_b64 s[10:11], 0
.LBB0_443:
	s_andn2_b64 vcc, exec, s[10:11]
	s_cbranch_vccnz .LBB0_440
	s_add_i32 s10, s67, s14
	s_ashr_i32 s11, s10, 31
	s_lshl_b64 s[10:11], s[10:11], 12
	s_add_u32 s10, s38, s10
	s_addc_u32 s11, s39, s11
	s_lshl_b32 s15, s59, 1
	s_add_u32 s10, s10, s15
	s_addc_u32 s11, s11, 0
	s_add_u32 s10, s10, s72
	s_addc_u32 s11, s11, 0
	s_add_u32 s10, s10, 0x4500800
	s_addc_u32 s11, s11, 0
	v_cvt_f16_f32_e32 v34, v42
	v_cvt_f16_f32_e32 v35, v43
	v_cvt_f16_f32_e32 v36, v44
	v_cvt_f16_f32_e32 v37, v45
	v_cvt_f16_f32_e32 v38, v46
	v_cvt_f16_f32_e32 v39, v47
	v_cvt_f16_f32_e32 v40, v48
	v_cvt_f16_f32_e32 v41, v49
	global_store_short v66, v34, s[10:11]
	global_store_short v68, v35, s[10:11]
	global_store_short v70, v36, s[10:11]
	global_store_short v72, v37, s[10:11]
	global_store_short v74, v38, s[10:11]
	global_store_short v76, v39, s[10:11]
	global_store_short v78, v40, s[10:11]
	global_store_short v80, v41, s[10:11]
	s_branch .LBB0_440
